# v41 + P0 folded odd out-proj tiles: scaled w_out rows in 128 VGPRs, pool_w quad-replicated 16-byte loads + quad_perm DPP fma (same fma order), 8 loads in flight
# speedup vs baseline: 1.0318x; 1.0318x over previous
.Lwf_fold:
	v_and_b32_e32 v29, 63, v155
	v_lshrrev_b32_e32 v24, 6, v155
	v_lshlrev_b32_e32 v26, 2, v29
	v_and_b32_e32 v28, 3, v155
	v_lshlrev_b32_e32 v29, 1, v29
	v_readfirstlane_b32 s58, v24
	v_lshlrev_b32_e32 v28, 4, v28
	s_add_i32 s8, s89, 0xfffffe80
	s_lshr_b32 s30, s8, 7
	s_and_b32 s8, s8, 0x7f
	s_and_b32 s9, s8, 7
	s_lshr_b32 s8, s8, 3
	s_mul_i32 s59, s30, 48
	s_add_u32 s10, s0, s59
	s_addc_u32 s11, s1, 0
	s_load_dwordx2 s[56:57], s[10:11], 0x100
	s_load_dwordx2 s[54:55], s[10:11], 0x110
	s_load_dwordx2 s[90:91], s[10:11], 0x118
	s_load_dwordx2 vcc, s[0:1], 0xf8
	s_lshl_b32 s58, s58, 4
	s_waitcnt lgkmcnt(0)
	s_lshl_b32 s59, s30, 2
	s_add_i32 s59, s59, s9
	s_lshl_b32 s10, s59, 7
	s_add_i32 s10, s10, s58
	s_lshl_b32 s10, s10, 9
	s_add_u32 s52, s24, s10
	s_addc_u32 s53, s25, 0
	global_load_dwordx4 v[10:13], v28, s[52:53] offset:0
	global_load_dwordx4 v[30:33], v28, s[52:53] offset:64
	global_load_dwordx4 v[34:37], v28, s[52:53] offset:128
	global_load_dwordx4 v[38:41], v28, s[52:53] offset:192
	global_load_dwordx4 v[42:45], v28, s[52:53] offset:256
	global_load_dwordx4 v[178:181], v28, s[52:53] offset:320
	global_load_dwordx4 v[182:185], v28, s[52:53] offset:384
	global_load_dwordx4 v[244:247], v28, s[52:53] offset:448
	s_lshl_b32 s10, s59, 9
	s_add_u32 s6, s26, s10
	s_addc_u32 s7, s27, 0
	s_load_dwordx16 s[36:51], s[6:7], 0x0
	s_lshl_b32 s10, s9, 7
	s_add_i32 s11, s10, s58
	s_mul_i32 s10, s10, s91
	s_lshl_b32 s59, s8, 6
	s_add_i32 s10, s10, s59
	s_lshl_b32 s10, s10, 2
	s_add_u32 s56, s56, s10
	s_addc_u32 s57, s57, 0
	s_mul_i32 s10, s59, s90
	s_add_i32 s10, s10, s11
	s_lshl_b32 s10, s10, 1
	s_add_u32 s54, s54, s10
	s_addc_u32 s55, s55, 0
	s_add_u32 s54, s54, vcc_lo
	s_addc_u32 s55, s55, vcc_hi
	v_mul_u32_u24_e32 v27, s90, v29
	s_lshl_b32 s91, s91, 2
	global_load_dword v46, v26, s[56:57]
	s_add_u32 s56, s56, s91
	s_addc_u32 s57, s57, 0
	global_load_dword v47, v26, s[56:57]
	s_add_u32 s56, s56, s91
	s_addc_u32 s57, s57, 0
	global_load_dword v48, v26, s[56:57]
	s_add_u32 s56, s56, s91
	s_addc_u32 s57, s57, 0
	global_load_dword v49, v26, s[56:57]
	s_add_u32 s56, s56, s91
	s_addc_u32 s57, s57, 0
	global_load_dword v50, v26, s[56:57]
	s_add_u32 s56, s56, s91
	s_addc_u32 s57, s57, 0
	global_load_dword v51, v26, s[56:57]
	s_add_u32 s56, s56, s91
	s_addc_u32 s57, s57, 0
	global_load_dword v52, v26, s[56:57]
	s_add_u32 s56, s56, s91
	s_addc_u32 s57, s57, 0
	global_load_dword v53, v26, s[56:57]
	s_add_u32 s56, s56, s91
	s_addc_u32 s57, s57, 0
	global_load_dword v54, v26, s[56:57]
	s_add_u32 s56, s56, s91
	s_addc_u32 s57, s57, 0
	global_load_dword v55, v26, s[56:57]
	s_add_u32 s56, s56, s91
	s_addc_u32 s57, s57, 0
	global_load_dword v56, v26, s[56:57]
	s_add_u32 s56, s56, s91
	s_addc_u32 s57, s57, 0
	global_load_dword v57, v26, s[56:57]
	s_add_u32 s56, s56, s91
	s_addc_u32 s57, s57, 0
	global_load_dword v58, v26, s[56:57]
	s_add_u32 s56, s56, s91
	s_addc_u32 s57, s57, 0
	global_load_dword v59, v26, s[56:57]
	s_add_u32 s56, s56, s91
	s_addc_u32 s57, s57, 0
	global_load_dword v60, v26, s[56:57]
	s_add_u32 s56, s56, s91
	s_addc_u32 s57, s57, 0
	global_load_dword v61, v26, s[56:57]
	s_add_u32 s56, s56, s91
	s_addc_u32 s57, s57, 0
	s_load_dwordx16 s[68:83], s[6:7], 0x40
	global_load_dword v62, v26, s[56:57]
	s_add_u32 s56, s56, s91
	s_addc_u32 s57, s57, 0
	global_load_dword v63, v26, s[56:57]
	s_add_u32 s56, s56, s91
	s_addc_u32 s57, s57, 0
	global_load_dword v64, v26, s[56:57]
	s_add_u32 s56, s56, s91
	s_addc_u32 s57, s57, 0
	global_load_dword v65, v26, s[56:57]
	s_add_u32 s56, s56, s91
	s_addc_u32 s57, s57, 0
	global_load_dword v66, v26, s[56:57]
	s_add_u32 s56, s56, s91
	s_addc_u32 s57, s57, 0
	global_load_dword v67, v26, s[56:57]
	s_add_u32 s56, s56, s91
	s_addc_u32 s57, s57, 0
	global_load_dword v68, v26, s[56:57]
	s_add_u32 s56, s56, s91
	s_addc_u32 s57, s57, 0
	global_load_dword v69, v26, s[56:57]
	s_add_u32 s56, s56, s91
	s_addc_u32 s57, s57, 0
	global_load_dword v70, v26, s[56:57]
	s_add_u32 s56, s56, s91
	s_addc_u32 s57, s57, 0
	global_load_dword v71, v26, s[56:57]
	s_add_u32 s56, s56, s91
	s_addc_u32 s57, s57, 0
	global_load_dword v72, v26, s[56:57]
	s_add_u32 s56, s56, s91
	s_addc_u32 s57, s57, 0
	global_load_dword v73, v26, s[56:57]
	s_add_u32 s56, s56, s91
	s_addc_u32 s57, s57, 0
	global_load_dword v74, v26, s[56:57]
	s_add_u32 s56, s56, s91
	s_addc_u32 s57, s57, 0
	global_load_dword v75, v26, s[56:57]
	s_add_u32 s56, s56, s91
	s_addc_u32 s57, s57, 0
	global_load_dword v76, v26, s[56:57]
	s_add_u32 s56, s56, s91
	s_addc_u32 s57, s57, 0
	global_load_dword v77, v26, s[56:57]
	s_add_u32 s56, s56, s91
	s_addc_u32 s57, s57, 0
	global_load_dword v78, v26, s[56:57]
	s_add_u32 s56, s56, s91
	s_addc_u32 s57, s57, 0
	global_load_dword v79, v26, s[56:57]
	s_add_u32 s56, s56, s91
	s_addc_u32 s57, s57, 0
	global_load_dword v80, v26, s[56:57]
	s_add_u32 s56, s56, s91
	s_addc_u32 s57, s57, 0
	global_load_dword v81, v26, s[56:57]
	s_add_u32 s56, s56, s91
	s_addc_u32 s57, s57, 0
	global_load_dword v82, v26, s[56:57]
	s_add_u32 s56, s56, s91
	s_addc_u32 s57, s57, 0
	global_load_dword v83, v26, s[56:57]
	s_add_u32 s56, s56, s91
	s_addc_u32 s57, s57, 0
	global_load_dword v85, v26, s[56:57]
	s_add_u32 s56, s56, s91
	s_addc_u32 s57, s57, 0
	global_load_dword v86, v26, s[56:57]
	s_add_u32 s56, s56, s91
	s_addc_u32 s57, s57, 0
	global_load_dword v87, v26, s[56:57]
	s_add_u32 s56, s56, s91
	s_addc_u32 s57, s57, 0
	global_load_dword v88, v26, s[56:57]
	s_add_u32 s56, s56, s91
	s_addc_u32 s57, s57, 0
	global_load_dword v89, v26, s[56:57]
	s_add_u32 s56, s56, s91
	s_addc_u32 s57, s57, 0
	global_load_dword v90, v26, s[56:57]
	s_add_u32 s56, s56, s91
	s_addc_u32 s57, s57, 0
	global_load_dword v91, v26, s[56:57]
	s_add_u32 s56, s56, s91
	s_addc_u32 s57, s57, 0
	global_load_dword v92, v26, s[56:57]
	s_add_u32 s56, s56, s91
	s_addc_u32 s57, s57, 0
	global_load_dword v93, v26, s[56:57]
	s_add_u32 s56, s56, s91
	s_addc_u32 s57, s57, 0
	global_load_dword v94, v26, s[56:57]
	s_add_u32 s56, s56, s91
	s_addc_u32 s57, s57, 0
	s_waitcnt vmcnt(32) lgkmcnt(0)
	v_mul_f32_e32 v46, s36, v46
	v_mul_f32_e32 v47, s37, v47
	v_mul_f32_e32 v48, s38, v48
	v_mul_f32_e32 v49, s39, v49
	v_mul_f32_e32 v50, s40, v50
	v_mul_f32_e32 v51, s41, v51
	v_mul_f32_e32 v52, s42, v52
	v_mul_f32_e32 v53, s43, v53
	v_mul_f32_e32 v54, s44, v54
	v_mul_f32_e32 v55, s45, v55
	v_mul_f32_e32 v56, s46, v56
	v_mul_f32_e32 v57, s47, v57
	v_mul_f32_e32 v58, s48, v58
	v_mul_f32_e32 v59, s49, v59
	v_mul_f32_e32 v60, s50, v60
	v_mul_f32_e32 v61, s51, v61
	s_load_dwordx16 s[36:51], s[6:7], 0x80
	global_load_dword v95, v26, s[56:57]
	s_add_u32 s56, s56, s91
	s_addc_u32 s57, s57, 0
	global_load_dword v96, v26, s[56:57]
	s_add_u32 s56, s56, s91
	s_addc_u32 s57, s57, 0
	global_load_dword v97, v26, s[56:57]
	s_add_u32 s56, s56, s91
	s_addc_u32 s57, s57, 0
	global_load_dword v98, v26, s[56:57]
	s_add_u32 s56, s56, s91
	s_addc_u32 s57, s57, 0
	global_load_dword v99, v26, s[56:57]
	s_add_u32 s56, s56, s91
	s_addc_u32 s57, s57, 0
	global_load_dword v100, v26, s[56:57]
	s_add_u32 s56, s56, s91
	s_addc_u32 s57, s57, 0
	global_load_dword v101, v26, s[56:57]
	s_add_u32 s56, s56, s91
	s_addc_u32 s57, s57, 0
	global_load_dword v102, v26, s[56:57]
	s_add_u32 s56, s56, s91
	s_addc_u32 s57, s57, 0
	global_load_dword v103, v26, s[56:57]
	s_add_u32 s56, s56, s91
	s_addc_u32 s57, s57, 0
	global_load_dword v104, v26, s[56:57]
	s_add_u32 s56, s56, s91
	s_addc_u32 s57, s57, 0
	global_load_dword v105, v26, s[56:57]
	s_add_u32 s56, s56, s91
	s_addc_u32 s57, s57, 0
	global_load_dword v106, v26, s[56:57]
	s_add_u32 s56, s56, s91
	s_addc_u32 s57, s57, 0
	global_load_dword v107, v26, s[56:57]
	s_add_u32 s56, s56, s91
	s_addc_u32 s57, s57, 0
	global_load_dword v108, v26, s[56:57]
	s_add_u32 s56, s56, s91
	s_addc_u32 s57, s57, 0
	global_load_dword v109, v26, s[56:57]
	s_add_u32 s56, s56, s91
	s_addc_u32 s57, s57, 0
	global_load_dword v110, v26, s[56:57]
	s_add_u32 s56, s56, s91
	s_addc_u32 s57, s57, 0
	s_waitcnt vmcnt(32) lgkmcnt(0)
	v_mul_f32_e32 v62, s68, v62
	v_mul_f32_e32 v63, s69, v63
	v_mul_f32_e32 v64, s70, v64
	v_mul_f32_e32 v65, s71, v65
	v_mul_f32_e32 v66, s72, v66
	v_mul_f32_e32 v67, s73, v67
	v_mul_f32_e32 v68, s74, v68
	v_mul_f32_e32 v69, s75, v69
	v_mul_f32_e32 v70, s76, v70
	v_mul_f32_e32 v71, s77, v71
	v_mul_f32_e32 v72, s78, v72
	v_mul_f32_e32 v73, s79, v73
	v_mul_f32_e32 v74, s80, v74
	v_mul_f32_e32 v75, s81, v75
	v_mul_f32_e32 v76, s82, v76
	v_mul_f32_e32 v77, s83, v77
	s_load_dwordx16 s[68:83], s[6:7], 0xc0
	global_load_dword v111, v26, s[56:57]
	s_add_u32 s56, s56, s91
	s_addc_u32 s57, s57, 0
	global_load_dword v112, v26, s[56:57]
	s_add_u32 s56, s56, s91
	s_addc_u32 s57, s57, 0
	global_load_dword v113, v26, s[56:57]
	s_add_u32 s56, s56, s91
	s_addc_u32 s57, s57, 0
	global_load_dword v114, v26, s[56:57]
	s_add_u32 s56, s56, s91
	s_addc_u32 s57, s57, 0
	global_load_dword v115, v26, s[56:57]
	s_add_u32 s56, s56, s91
	s_addc_u32 s57, s57, 0
	global_load_dword v116, v26, s[56:57]
	s_add_u32 s56, s56, s91
	s_addc_u32 s57, s57, 0
	global_load_dword v117, v26, s[56:57]
	s_add_u32 s56, s56, s91
	s_addc_u32 s57, s57, 0
	global_load_dword v118, v26, s[56:57]
	s_add_u32 s56, s56, s91
	s_addc_u32 s57, s57, 0
	global_load_dword v119, v26, s[56:57]
	s_add_u32 s56, s56, s91
	s_addc_u32 s57, s57, 0
	global_load_dword v120, v26, s[56:57]
	s_add_u32 s56, s56, s91
	s_addc_u32 s57, s57, 0
	global_load_dword v121, v26, s[56:57]
	s_add_u32 s56, s56, s91
	s_addc_u32 s57, s57, 0
	global_load_dword v122, v26, s[56:57]
	s_add_u32 s56, s56, s91
	s_addc_u32 s57, s57, 0
	global_load_dword v123, v26, s[56:57]
	s_add_u32 s56, s56, s91
	s_addc_u32 s57, s57, 0
	global_load_dword v124, v26, s[56:57]
	s_add_u32 s56, s56, s91
	s_addc_u32 s57, s57, 0
	global_load_dword v125, v26, s[56:57]
	s_add_u32 s56, s56, s91
	s_addc_u32 s57, s57, 0
	global_load_dword v126, v26, s[56:57]
	s_add_u32 s56, s56, s91
	s_addc_u32 s57, s57, 0
	s_waitcnt vmcnt(32) lgkmcnt(0)
	v_mul_f32_e32 v78, s36, v78
	v_mul_f32_e32 v79, s37, v79
	v_mul_f32_e32 v80, s38, v80
	v_mul_f32_e32 v81, s39, v81
	v_mul_f32_e32 v82, s40, v82
	v_mul_f32_e32 v83, s41, v83
	v_mul_f32_e32 v85, s42, v85
	v_mul_f32_e32 v86, s43, v86
	v_mul_f32_e32 v87, s44, v87
	v_mul_f32_e32 v88, s45, v88
	v_mul_f32_e32 v89, s46, v89
	v_mul_f32_e32 v90, s47, v90
	v_mul_f32_e32 v91, s48, v91
	v_mul_f32_e32 v92, s49, v92
	v_mul_f32_e32 v93, s50, v93
	v_mul_f32_e32 v94, s51, v94
	s_load_dwordx16 s[36:51], s[6:7], 0x100
	global_load_dword v127, v26, s[56:57]
	s_add_u32 s56, s56, s91
	s_addc_u32 s57, s57, 0
	global_load_dword v128, v26, s[56:57]
	s_add_u32 s56, s56, s91
	s_addc_u32 s57, s57, 0
	global_load_dword v129, v26, s[56:57]
	s_add_u32 s56, s56, s91
	s_addc_u32 s57, s57, 0
	global_load_dword v130, v26, s[56:57]
	s_add_u32 s56, s56, s91
	s_addc_u32 s57, s57, 0
	global_load_dword v131, v26, s[56:57]
	s_add_u32 s56, s56, s91
	s_addc_u32 s57, s57, 0
	global_load_dword v132, v26, s[56:57]
	s_add_u32 s56, s56, s91
	s_addc_u32 s57, s57, 0
	global_load_dword v133, v26, s[56:57]
	s_add_u32 s56, s56, s91
	s_addc_u32 s57, s57, 0
	global_load_dword v134, v26, s[56:57]
	s_add_u32 s56, s56, s91
	s_addc_u32 s57, s57, 0
	global_load_dword v135, v26, s[56:57]
	s_add_u32 s56, s56, s91
	s_addc_u32 s57, s57, 0
	global_load_dword v136, v26, s[56:57]
	s_add_u32 s56, s56, s91
	s_addc_u32 s57, s57, 0
	global_load_dword v137, v26, s[56:57]
	s_add_u32 s56, s56, s91
	s_addc_u32 s57, s57, 0
	global_load_dword v140, v26, s[56:57]
	s_add_u32 s56, s56, s91
	s_addc_u32 s57, s57, 0
	global_load_dword v141, v26, s[56:57]
	s_add_u32 s56, s56, s91
	s_addc_u32 s57, s57, 0
	global_load_dword v142, v26, s[56:57]
	s_add_u32 s56, s56, s91
	s_addc_u32 s57, s57, 0
	global_load_dword v143, v26, s[56:57]
	s_add_u32 s56, s56, s91
	s_addc_u32 s57, s57, 0
	global_load_dword v144, v26, s[56:57]
	s_add_u32 s56, s56, s91
	s_addc_u32 s57, s57, 0
	s_waitcnt vmcnt(32) lgkmcnt(0)
	v_mul_f32_e32 v95, s68, v95
	v_mul_f32_e32 v96, s69, v96
	v_mul_f32_e32 v97, s70, v97
	v_mul_f32_e32 v98, s71, v98
	v_mul_f32_e32 v99, s72, v99
	v_mul_f32_e32 v100, s73, v100
	v_mul_f32_e32 v101, s74, v101
	v_mul_f32_e32 v102, s75, v102
	v_mul_f32_e32 v103, s76, v103
	v_mul_f32_e32 v104, s77, v104
	v_mul_f32_e32 v105, s78, v105
	v_mul_f32_e32 v106, s79, v106
	v_mul_f32_e32 v107, s80, v107
	v_mul_f32_e32 v108, s81, v108
	v_mul_f32_e32 v109, s82, v109
	v_mul_f32_e32 v110, s83, v110
	s_load_dwordx16 s[68:83], s[6:7], 0x140
	global_load_dword v145, v26, s[56:57]
	s_add_u32 s56, s56, s91
	s_addc_u32 s57, s57, 0
	global_load_dword v146, v26, s[56:57]
	s_add_u32 s56, s56, s91
	s_addc_u32 s57, s57, 0
	global_load_dword v147, v26, s[56:57]
	s_add_u32 s56, s56, s91
	s_addc_u32 s57, s57, 0
	global_load_dword v148, v26, s[56:57]
	s_add_u32 s56, s56, s91
	s_addc_u32 s57, s57, 0
	global_load_dword v149, v26, s[56:57]
	s_add_u32 s56, s56, s91
	s_addc_u32 s57, s57, 0
	global_load_dword v150, v26, s[56:57]
	s_add_u32 s56, s56, s91
	s_addc_u32 s57, s57, 0
	global_load_dword v151, v26, s[56:57]
	s_add_u32 s56, s56, s91
	s_addc_u32 s57, s57, 0
	global_load_dword v152, v26, s[56:57]
	s_add_u32 s56, s56, s91
	s_addc_u32 s57, s57, 0
	global_load_dword v153, v26, s[56:57]
	s_add_u32 s56, s56, s91
	s_addc_u32 s57, s57, 0
	global_load_dword v154, v26, s[56:57]
	s_add_u32 s56, s56, s91
	s_addc_u32 s57, s57, 0
	global_load_dword v156, v26, s[56:57]
	s_add_u32 s56, s56, s91
	s_addc_u32 s57, s57, 0
	global_load_dword v157, v26, s[56:57]
	s_add_u32 s56, s56, s91
	s_addc_u32 s57, s57, 0
	global_load_dword v158, v26, s[56:57]
	s_add_u32 s56, s56, s91
	s_addc_u32 s57, s57, 0
	global_load_dword v159, v26, s[56:57]
	s_add_u32 s56, s56, s91
	s_addc_u32 s57, s57, 0
	global_load_dword v160, v26, s[56:57]
	s_add_u32 s56, s56, s91
	s_addc_u32 s57, s57, 0
	global_load_dword v161, v26, s[56:57]
	s_add_u32 s56, s56, s91
	s_addc_u32 s57, s57, 0
	s_waitcnt vmcnt(32) lgkmcnt(0)
	v_mul_f32_e32 v111, s36, v111
	v_mul_f32_e32 v112, s37, v112
	v_mul_f32_e32 v113, s38, v113
	v_mul_f32_e32 v114, s39, v114
	v_mul_f32_e32 v115, s40, v115
	v_mul_f32_e32 v116, s41, v116
	v_mul_f32_e32 v117, s42, v117
	v_mul_f32_e32 v118, s43, v118
	v_mul_f32_e32 v119, s44, v119
	v_mul_f32_e32 v120, s45, v120
	v_mul_f32_e32 v121, s46, v121
	v_mul_f32_e32 v122, s47, v122
	v_mul_f32_e32 v123, s48, v123
	v_mul_f32_e32 v124, s49, v124
	v_mul_f32_e32 v125, s50, v125
	v_mul_f32_e32 v126, s51, v126
	s_load_dwordx16 s[36:51], s[6:7], 0x180
	global_load_dword v162, v26, s[56:57]
	s_add_u32 s56, s56, s91
	s_addc_u32 s57, s57, 0
	global_load_dword v163, v26, s[56:57]
	s_add_u32 s56, s56, s91
	s_addc_u32 s57, s57, 0
	global_load_dword v164, v26, s[56:57]
	s_add_u32 s56, s56, s91
	s_addc_u32 s57, s57, 0
	global_load_dword v165, v26, s[56:57]
	s_add_u32 s56, s56, s91
	s_addc_u32 s57, s57, 0
	global_load_dword v166, v26, s[56:57]
	s_add_u32 s56, s56, s91
	s_addc_u32 s57, s57, 0
	global_load_dword v167, v26, s[56:57]
	s_add_u32 s56, s56, s91
	s_addc_u32 s57, s57, 0
	global_load_dword v168, v26, s[56:57]
	s_add_u32 s56, s56, s91
	s_addc_u32 s57, s57, 0
	global_load_dword v169, v26, s[56:57]
	s_add_u32 s56, s56, s91
	s_addc_u32 s57, s57, 0
	global_load_dword v170, v26, s[56:57]
	s_add_u32 s56, s56, s91
	s_addc_u32 s57, s57, 0
	global_load_dword v171, v26, s[56:57]
	s_add_u32 s56, s56, s91
	s_addc_u32 s57, s57, 0
	global_load_dword v172, v26, s[56:57]
	s_add_u32 s56, s56, s91
	s_addc_u32 s57, s57, 0
	global_load_dword v173, v26, s[56:57]
	s_add_u32 s56, s56, s91
	s_addc_u32 s57, s57, 0
	global_load_dword v174, v26, s[56:57]
	s_add_u32 s56, s56, s91
	s_addc_u32 s57, s57, 0
	global_load_dword v175, v26, s[56:57]
	s_add_u32 s56, s56, s91
	s_addc_u32 s57, s57, 0
	global_load_dword v176, v26, s[56:57]
	s_add_u32 s56, s56, s91
	s_addc_u32 s57, s57, 0
	global_load_dword v177, v26, s[56:57]
	s_waitcnt vmcnt(32) lgkmcnt(0)
	v_mul_f32_e32 v127, s68, v127
	v_mul_f32_e32 v128, s69, v128
	v_mul_f32_e32 v129, s70, v129
	v_mul_f32_e32 v130, s71, v130
	v_mul_f32_e32 v131, s72, v131
	v_mul_f32_e32 v132, s73, v132
	v_mul_f32_e32 v133, s74, v133
	v_mul_f32_e32 v134, s75, v134
	v_mul_f32_e32 v135, s76, v135
	v_mul_f32_e32 v136, s77, v136
	v_mul_f32_e32 v137, s78, v137
	v_mul_f32_e32 v140, s79, v140
	v_mul_f32_e32 v141, s80, v141
	v_mul_f32_e32 v142, s81, v142
	v_mul_f32_e32 v143, s82, v143
	v_mul_f32_e32 v144, s83, v144
	s_load_dwordx16 s[68:83], s[6:7], 0x1c0
	s_waitcnt vmcnt(16) lgkmcnt(0)
	v_mul_f32_e32 v145, s36, v145
	v_mul_f32_e32 v146, s37, v146
	v_mul_f32_e32 v147, s38, v147
	v_mul_f32_e32 v148, s39, v148
	v_mul_f32_e32 v149, s40, v149
	v_mul_f32_e32 v150, s41, v150
	v_mul_f32_e32 v151, s42, v151
	v_mul_f32_e32 v152, s43, v152
	v_mul_f32_e32 v153, s44, v153
	v_mul_f32_e32 v154, s45, v154
	v_mul_f32_e32 v156, s46, v156
	v_mul_f32_e32 v157, s47, v157
	v_mul_f32_e32 v158, s48, v158
	v_mul_f32_e32 v159, s49, v159
	v_mul_f32_e32 v160, s50, v160
	v_mul_f32_e32 v161, s51, v161
	s_waitcnt vmcnt(0)
	v_mul_f32_e32 v162, s68, v162
	v_mul_f32_e32 v163, s69, v163
	v_mul_f32_e32 v164, s70, v164
	v_mul_f32_e32 v165, s71, v165
	v_mul_f32_e32 v166, s72, v166
	v_mul_f32_e32 v167, s73, v167
	v_mul_f32_e32 v168, s74, v168
	v_mul_f32_e32 v169, s75, v169
	v_mul_f32_e32 v170, s76, v170
	v_mul_f32_e32 v171, s77, v171
	v_mul_f32_e32 v172, s78, v172
	v_mul_f32_e32 v173, s79, v173
	v_mul_f32_e32 v174, s80, v174
	v_mul_f32_e32 v175, s81, v175
	v_mul_f32_e32 v176, s82, v176
	v_mul_f32_e32 v177, s83, v177
	s_mov_b32 s30, 0
.Lwf_fold_loop:
	v_mov_b32_e32 v0, 0
	s_add_u32 s8, s52, 0x200
	s_addc_u32 s9, s53, 0
	s_waitcnt vmcnt(7)
	v_fmac_f32_dpp v0, v10, v46 quad_perm:[0,0,0,0] row_mask:0xf bank_mask:0xf
	v_fmac_f32_dpp v0, v11, v47 quad_perm:[0,0,0,0] row_mask:0xf bank_mask:0xf
	v_fmac_f32_dpp v0, v12, v48 quad_perm:[0,0,0,0] row_mask:0xf bank_mask:0xf
	v_fmac_f32_dpp v0, v13, v49 quad_perm:[0,0,0,0] row_mask:0xf bank_mask:0xf
	v_fmac_f32_dpp v0, v10, v50 quad_perm:[1,1,1,1] row_mask:0xf bank_mask:0xf
	v_fmac_f32_dpp v0, v11, v51 quad_perm:[1,1,1,1] row_mask:0xf bank_mask:0xf
	v_fmac_f32_dpp v0, v12, v52 quad_perm:[1,1,1,1] row_mask:0xf bank_mask:0xf
	v_fmac_f32_dpp v0, v13, v53 quad_perm:[1,1,1,1] row_mask:0xf bank_mask:0xf
	v_fmac_f32_dpp v0, v10, v54 quad_perm:[2,2,2,2] row_mask:0xf bank_mask:0xf
	v_fmac_f32_dpp v0, v11, v55 quad_perm:[2,2,2,2] row_mask:0xf bank_mask:0xf
	v_fmac_f32_dpp v0, v12, v56 quad_perm:[2,2,2,2] row_mask:0xf bank_mask:0xf
	v_fmac_f32_dpp v0, v13, v57 quad_perm:[2,2,2,2] row_mask:0xf bank_mask:0xf
	v_fmac_f32_dpp v0, v10, v58 quad_perm:[3,3,3,3] row_mask:0xf bank_mask:0xf
	v_fmac_f32_dpp v0, v11, v59 quad_perm:[3,3,3,3] row_mask:0xf bank_mask:0xf
	v_fmac_f32_dpp v0, v12, v60 quad_perm:[3,3,3,3] row_mask:0xf bank_mask:0xf
	v_fmac_f32_dpp v0, v13, v61 quad_perm:[3,3,3,3] row_mask:0xf bank_mask:0xf
	global_load_dwordx4 v[10:13], v28, s[8:9] offset:0
	s_waitcnt vmcnt(7)
	v_fmac_f32_dpp v0, v30, v62 quad_perm:[0,0,0,0] row_mask:0xf bank_mask:0xf
	v_fmac_f32_dpp v0, v31, v63 quad_perm:[0,0,0,0] row_mask:0xf bank_mask:0xf
	v_fmac_f32_dpp v0, v32, v64 quad_perm:[0,0,0,0] row_mask:0xf bank_mask:0xf
	v_fmac_f32_dpp v0, v33, v65 quad_perm:[0,0,0,0] row_mask:0xf bank_mask:0xf
	v_fmac_f32_dpp v0, v30, v66 quad_perm:[1,1,1,1] row_mask:0xf bank_mask:0xf
	v_fmac_f32_dpp v0, v31, v67 quad_perm:[1,1,1,1] row_mask:0xf bank_mask:0xf
	v_fmac_f32_dpp v0, v32, v68 quad_perm:[1,1,1,1] row_mask:0xf bank_mask:0xf
	v_fmac_f32_dpp v0, v33, v69 quad_perm:[1,1,1,1] row_mask:0xf bank_mask:0xf
	v_fmac_f32_dpp v0, v30, v70 quad_perm:[2,2,2,2] row_mask:0xf bank_mask:0xf
	v_fmac_f32_dpp v0, v31, v71 quad_perm:[2,2,2,2] row_mask:0xf bank_mask:0xf
	v_fmac_f32_dpp v0, v32, v72 quad_perm:[2,2,2,2] row_mask:0xf bank_mask:0xf
	v_fmac_f32_dpp v0, v33, v73 quad_perm:[2,2,2,2] row_mask:0xf bank_mask:0xf
	v_fmac_f32_dpp v0, v30, v74 quad_perm:[3,3,3,3] row_mask:0xf bank_mask:0xf
	v_fmac_f32_dpp v0, v31, v75 quad_perm:[3,3,3,3] row_mask:0xf bank_mask:0xf
	v_fmac_f32_dpp v0, v32, v76 quad_perm:[3,3,3,3] row_mask:0xf bank_mask:0xf
	v_fmac_f32_dpp v0, v33, v77 quad_perm:[3,3,3,3] row_mask:0xf bank_mask:0xf
	global_load_dwordx4 v[30:33], v28, s[8:9] offset:64
	s_waitcnt vmcnt(7)
	v_fmac_f32_dpp v0, v34, v78 quad_perm:[0,0,0,0] row_mask:0xf bank_mask:0xf
	v_fmac_f32_dpp v0, v35, v79 quad_perm:[0,0,0,0] row_mask:0xf bank_mask:0xf
	v_fmac_f32_dpp v0, v36, v80 quad_perm:[0,0,0,0] row_mask:0xf bank_mask:0xf
	v_fmac_f32_dpp v0, v37, v81 quad_perm:[0,0,0,0] row_mask:0xf bank_mask:0xf
	v_fmac_f32_dpp v0, v34, v82 quad_perm:[1,1,1,1] row_mask:0xf bank_mask:0xf
	v_fmac_f32_dpp v0, v35, v83 quad_perm:[1,1,1,1] row_mask:0xf bank_mask:0xf
	v_fmac_f32_dpp v0, v36, v85 quad_perm:[1,1,1,1] row_mask:0xf bank_mask:0xf
	v_fmac_f32_dpp v0, v37, v86 quad_perm:[1,1,1,1] row_mask:0xf bank_mask:0xf
	v_fmac_f32_dpp v0, v34, v87 quad_perm:[2,2,2,2] row_mask:0xf bank_mask:0xf
	v_fmac_f32_dpp v0, v35, v88 quad_perm:[2,2,2,2] row_mask:0xf bank_mask:0xf
	v_fmac_f32_dpp v0, v36, v89 quad_perm:[2,2,2,2] row_mask:0xf bank_mask:0xf
	v_fmac_f32_dpp v0, v37, v90 quad_perm:[2,2,2,2] row_mask:0xf bank_mask:0xf
	v_fmac_f32_dpp v0, v34, v91 quad_perm:[3,3,3,3] row_mask:0xf bank_mask:0xf
	v_fmac_f32_dpp v0, v35, v92 quad_perm:[3,3,3,3] row_mask:0xf bank_mask:0xf
	v_fmac_f32_dpp v0, v36, v93 quad_perm:[3,3,3,3] row_mask:0xf bank_mask:0xf
	v_fmac_f32_dpp v0, v37, v94 quad_perm:[3,3,3,3] row_mask:0xf bank_mask:0xf
	global_load_dwordx4 v[34:37], v28, s[8:9] offset:128
	s_waitcnt vmcnt(7)
	v_fmac_f32_dpp v0, v38, v95 quad_perm:[0,0,0,0] row_mask:0xf bank_mask:0xf
	v_fmac_f32_dpp v0, v39, v96 quad_perm:[0,0,0,0] row_mask:0xf bank_mask:0xf
	v_fmac_f32_dpp v0, v40, v97 quad_perm:[0,0,0,0] row_mask:0xf bank_mask:0xf
	v_fmac_f32_dpp v0, v41, v98 quad_perm:[0,0,0,0] row_mask:0xf bank_mask:0xf
	v_fmac_f32_dpp v0, v38, v99 quad_perm:[1,1,1,1] row_mask:0xf bank_mask:0xf
	v_fmac_f32_dpp v0, v39, v100 quad_perm:[1,1,1,1] row_mask:0xf bank_mask:0xf
	v_fmac_f32_dpp v0, v40, v101 quad_perm:[1,1,1,1] row_mask:0xf bank_mask:0xf
	v_fmac_f32_dpp v0, v41, v102 quad_perm:[1,1,1,1] row_mask:0xf bank_mask:0xf
	v_fmac_f32_dpp v0, v38, v103 quad_perm:[2,2,2,2] row_mask:0xf bank_mask:0xf
	v_fmac_f32_dpp v0, v39, v104 quad_perm:[2,2,2,2] row_mask:0xf bank_mask:0xf
	v_fmac_f32_dpp v0, v40, v105 quad_perm:[2,2,2,2] row_mask:0xf bank_mask:0xf
	v_fmac_f32_dpp v0, v41, v106 quad_perm:[2,2,2,2] row_mask:0xf bank_mask:0xf
	v_fmac_f32_dpp v0, v38, v107 quad_perm:[3,3,3,3] row_mask:0xf bank_mask:0xf
	v_fmac_f32_dpp v0, v39, v108 quad_perm:[3,3,3,3] row_mask:0xf bank_mask:0xf
	v_fmac_f32_dpp v0, v40, v109 quad_perm:[3,3,3,3] row_mask:0xf bank_mask:0xf
	v_fmac_f32_dpp v0, v41, v110 quad_perm:[3,3,3,3] row_mask:0xf bank_mask:0xf
	global_load_dwordx4 v[38:41], v28, s[8:9] offset:192
	s_waitcnt vmcnt(7)
	v_fmac_f32_dpp v0, v42, v111 quad_perm:[0,0,0,0] row_mask:0xf bank_mask:0xf
	v_fmac_f32_dpp v0, v43, v112 quad_perm:[0,0,0,0] row_mask:0xf bank_mask:0xf
	v_fmac_f32_dpp v0, v44, v113 quad_perm:[0,0,0,0] row_mask:0xf bank_mask:0xf
	v_fmac_f32_dpp v0, v45, v114 quad_perm:[0,0,0,0] row_mask:0xf bank_mask:0xf
	v_fmac_f32_dpp v0, v42, v115 quad_perm:[1,1,1,1] row_mask:0xf bank_mask:0xf
	v_fmac_f32_dpp v0, v43, v116 quad_perm:[1,1,1,1] row_mask:0xf bank_mask:0xf
	v_fmac_f32_dpp v0, v44, v117 quad_perm:[1,1,1,1] row_mask:0xf bank_mask:0xf
	v_fmac_f32_dpp v0, v45, v118 quad_perm:[1,1,1,1] row_mask:0xf bank_mask:0xf
	v_fmac_f32_dpp v0, v42, v119 quad_perm:[2,2,2,2] row_mask:0xf bank_mask:0xf
	v_fmac_f32_dpp v0, v43, v120 quad_perm:[2,2,2,2] row_mask:0xf bank_mask:0xf
	v_fmac_f32_dpp v0, v44, v121 quad_perm:[2,2,2,2] row_mask:0xf bank_mask:0xf
	v_fmac_f32_dpp v0, v45, v122 quad_perm:[2,2,2,2] row_mask:0xf bank_mask:0xf
	v_fmac_f32_dpp v0, v42, v123 quad_perm:[3,3,3,3] row_mask:0xf bank_mask:0xf
	v_fmac_f32_dpp v0, v43, v124 quad_perm:[3,3,3,3] row_mask:0xf bank_mask:0xf
	v_fmac_f32_dpp v0, v44, v125 quad_perm:[3,3,3,3] row_mask:0xf bank_mask:0xf
	v_fmac_f32_dpp v0, v45, v126 quad_perm:[3,3,3,3] row_mask:0xf bank_mask:0xf
	global_load_dwordx4 v[42:45], v28, s[8:9] offset:256
	s_waitcnt vmcnt(7)
	v_fmac_f32_dpp v0, v178, v127 quad_perm:[0,0,0,0] row_mask:0xf bank_mask:0xf
	v_fmac_f32_dpp v0, v179, v128 quad_perm:[0,0,0,0] row_mask:0xf bank_mask:0xf
	v_fmac_f32_dpp v0, v180, v129 quad_perm:[0,0,0,0] row_mask:0xf bank_mask:0xf
	v_fmac_f32_dpp v0, v181, v130 quad_perm:[0,0,0,0] row_mask:0xf bank_mask:0xf
	v_fmac_f32_dpp v0, v178, v131 quad_perm:[1,1,1,1] row_mask:0xf bank_mask:0xf
	v_fmac_f32_dpp v0, v179, v132 quad_perm:[1,1,1,1] row_mask:0xf bank_mask:0xf
	v_fmac_f32_dpp v0, v180, v133 quad_perm:[1,1,1,1] row_mask:0xf bank_mask:0xf
	v_fmac_f32_dpp v0, v181, v134 quad_perm:[1,1,1,1] row_mask:0xf bank_mask:0xf
	v_fmac_f32_dpp v0, v178, v135 quad_perm:[2,2,2,2] row_mask:0xf bank_mask:0xf
	v_fmac_f32_dpp v0, v179, v136 quad_perm:[2,2,2,2] row_mask:0xf bank_mask:0xf
	v_fmac_f32_dpp v0, v180, v137 quad_perm:[2,2,2,2] row_mask:0xf bank_mask:0xf
	v_fmac_f32_dpp v0, v181, v140 quad_perm:[2,2,2,2] row_mask:0xf bank_mask:0xf
	v_fmac_f32_dpp v0, v178, v141 quad_perm:[3,3,3,3] row_mask:0xf bank_mask:0xf
	v_fmac_f32_dpp v0, v179, v142 quad_perm:[3,3,3,3] row_mask:0xf bank_mask:0xf
	v_fmac_f32_dpp v0, v180, v143 quad_perm:[3,3,3,3] row_mask:0xf bank_mask:0xf
	v_fmac_f32_dpp v0, v181, v144 quad_perm:[3,3,3,3] row_mask:0xf bank_mask:0xf
	global_load_dwordx4 v[178:181], v28, s[8:9] offset:320
	s_waitcnt vmcnt(7)
	v_fmac_f32_dpp v0, v182, v145 quad_perm:[0,0,0,0] row_mask:0xf bank_mask:0xf
	v_fmac_f32_dpp v0, v183, v146 quad_perm:[0,0,0,0] row_mask:0xf bank_mask:0xf
	v_fmac_f32_dpp v0, v184, v147 quad_perm:[0,0,0,0] row_mask:0xf bank_mask:0xf
	v_fmac_f32_dpp v0, v185, v148 quad_perm:[0,0,0,0] row_mask:0xf bank_mask:0xf
	v_fmac_f32_dpp v0, v182, v149 quad_perm:[1,1,1,1] row_mask:0xf bank_mask:0xf
	v_fmac_f32_dpp v0, v183, v150 quad_perm:[1,1,1,1] row_mask:0xf bank_mask:0xf
	v_fmac_f32_dpp v0, v184, v151 quad_perm:[1,1,1,1] row_mask:0xf bank_mask:0xf
	v_fmac_f32_dpp v0, v185, v152 quad_perm:[1,1,1,1] row_mask:0xf bank_mask:0xf
	v_fmac_f32_dpp v0, v182, v153 quad_perm:[2,2,2,2] row_mask:0xf bank_mask:0xf
	v_fmac_f32_dpp v0, v183, v154 quad_perm:[2,2,2,2] row_mask:0xf bank_mask:0xf
	v_fmac_f32_dpp v0, v184, v156 quad_perm:[2,2,2,2] row_mask:0xf bank_mask:0xf
	v_fmac_f32_dpp v0, v185, v157 quad_perm:[2,2,2,2] row_mask:0xf bank_mask:0xf
	v_fmac_f32_dpp v0, v182, v158 quad_perm:[3,3,3,3] row_mask:0xf bank_mask:0xf
	v_fmac_f32_dpp v0, v183, v159 quad_perm:[3,3,3,3] row_mask:0xf bank_mask:0xf
	v_fmac_f32_dpp v0, v184, v160 quad_perm:[3,3,3,3] row_mask:0xf bank_mask:0xf
	v_fmac_f32_dpp v0, v185, v161 quad_perm:[3,3,3,3] row_mask:0xf bank_mask:0xf
	global_load_dwordx4 v[182:185], v28, s[8:9] offset:384
	s_waitcnt vmcnt(7)
	v_fmac_f32_dpp v0, v244, v162 quad_perm:[0,0,0,0] row_mask:0xf bank_mask:0xf
	v_fmac_f32_dpp v0, v245, v163 quad_perm:[0,0,0,0] row_mask:0xf bank_mask:0xf
	v_fmac_f32_dpp v0, v246, v164 quad_perm:[0,0,0,0] row_mask:0xf bank_mask:0xf
	v_fmac_f32_dpp v0, v247, v165 quad_perm:[0,0,0,0] row_mask:0xf bank_mask:0xf
	v_fmac_f32_dpp v0, v244, v166 quad_perm:[1,1,1,1] row_mask:0xf bank_mask:0xf
	v_fmac_f32_dpp v0, v245, v167 quad_perm:[1,1,1,1] row_mask:0xf bank_mask:0xf
	v_fmac_f32_dpp v0, v246, v168 quad_perm:[1,1,1,1] row_mask:0xf bank_mask:0xf
	v_fmac_f32_dpp v0, v247, v169 quad_perm:[1,1,1,1] row_mask:0xf bank_mask:0xf
	v_fmac_f32_dpp v0, v244, v170 quad_perm:[2,2,2,2] row_mask:0xf bank_mask:0xf
	v_fmac_f32_dpp v0, v245, v171 quad_perm:[2,2,2,2] row_mask:0xf bank_mask:0xf
	v_fmac_f32_dpp v0, v246, v172 quad_perm:[2,2,2,2] row_mask:0xf bank_mask:0xf
	v_fmac_f32_dpp v0, v247, v173 quad_perm:[2,2,2,2] row_mask:0xf bank_mask:0xf
	v_fmac_f32_dpp v0, v244, v174 quad_perm:[3,3,3,3] row_mask:0xf bank_mask:0xf
	v_fmac_f32_dpp v0, v245, v175 quad_perm:[3,3,3,3] row_mask:0xf bank_mask:0xf
	v_fmac_f32_dpp v0, v246, v176 quad_perm:[3,3,3,3] row_mask:0xf bank_mask:0xf
	v_fmac_f32_dpp v0, v247, v177 quad_perm:[3,3,3,3] row_mask:0xf bank_mask:0xf
	global_load_dwordx4 v[244:247], v28, s[8:9] offset:448
	v_mov_b32_e32 v1, 0
	s_movk_i32 s11, 0x200
	s_cmp_eq_u32 s30, 7
	s_cselect_b32 s10, s11, 0x400
	s_add_u32 s8, s52, s10
	s_addc_u32 s9, s53, 0
	s_waitcnt vmcnt(7)
	v_fmac_f32_dpp v1, v10, v46 quad_perm:[0,0,0,0] row_mask:0xf bank_mask:0xf
	v_fmac_f32_dpp v1, v11, v47 quad_perm:[0,0,0,0] row_mask:0xf bank_mask:0xf
	v_fmac_f32_dpp v1, v12, v48 quad_perm:[0,0,0,0] row_mask:0xf bank_mask:0xf
	v_fmac_f32_dpp v1, v13, v49 quad_perm:[0,0,0,0] row_mask:0xf bank_mask:0xf
	v_fmac_f32_dpp v1, v10, v50 quad_perm:[1,1,1,1] row_mask:0xf bank_mask:0xf
	v_fmac_f32_dpp v1, v11, v51 quad_perm:[1,1,1,1] row_mask:0xf bank_mask:0xf
	v_fmac_f32_dpp v1, v12, v52 quad_perm:[1,1,1,1] row_mask:0xf bank_mask:0xf
	v_fmac_f32_dpp v1, v13, v53 quad_perm:[1,1,1,1] row_mask:0xf bank_mask:0xf
	v_fmac_f32_dpp v1, v10, v54 quad_perm:[2,2,2,2] row_mask:0xf bank_mask:0xf
	v_fmac_f32_dpp v1, v11, v55 quad_perm:[2,2,2,2] row_mask:0xf bank_mask:0xf
	v_fmac_f32_dpp v1, v12, v56 quad_perm:[2,2,2,2] row_mask:0xf bank_mask:0xf
	v_fmac_f32_dpp v1, v13, v57 quad_perm:[2,2,2,2] row_mask:0xf bank_mask:0xf
	v_fmac_f32_dpp v1, v10, v58 quad_perm:[3,3,3,3] row_mask:0xf bank_mask:0xf
	v_fmac_f32_dpp v1, v11, v59 quad_perm:[3,3,3,3] row_mask:0xf bank_mask:0xf
	v_fmac_f32_dpp v1, v12, v60 quad_perm:[3,3,3,3] row_mask:0xf bank_mask:0xf
	v_fmac_f32_dpp v1, v13, v61 quad_perm:[3,3,3,3] row_mask:0xf bank_mask:0xf
	global_load_dwordx4 v[10:13], v28, s[8:9] offset:0
	s_waitcnt vmcnt(7)
	v_fmac_f32_dpp v1, v30, v62 quad_perm:[0,0,0,0] row_mask:0xf bank_mask:0xf
	v_fmac_f32_dpp v1, v31, v63 quad_perm:[0,0,0,0] row_mask:0xf bank_mask:0xf
	v_fmac_f32_dpp v1, v32, v64 quad_perm:[0,0,0,0] row_mask:0xf bank_mask:0xf
	v_fmac_f32_dpp v1, v33, v65 quad_perm:[0,0,0,0] row_mask:0xf bank_mask:0xf
	v_fmac_f32_dpp v1, v30, v66 quad_perm:[1,1,1,1] row_mask:0xf bank_mask:0xf
	v_fmac_f32_dpp v1, v31, v67 quad_perm:[1,1,1,1] row_mask:0xf bank_mask:0xf
	v_fmac_f32_dpp v1, v32, v68 quad_perm:[1,1,1,1] row_mask:0xf bank_mask:0xf
	v_fmac_f32_dpp v1, v33, v69 quad_perm:[1,1,1,1] row_mask:0xf bank_mask:0xf
	v_fmac_f32_dpp v1, v30, v70 quad_perm:[2,2,2,2] row_mask:0xf bank_mask:0xf
	v_fmac_f32_dpp v1, v31, v71 quad_perm:[2,2,2,2] row_mask:0xf bank_mask:0xf
	v_fmac_f32_dpp v1, v32, v72 quad_perm:[2,2,2,2] row_mask:0xf bank_mask:0xf
	v_fmac_f32_dpp v1, v33, v73 quad_perm:[2,2,2,2] row_mask:0xf bank_mask:0xf
	v_fmac_f32_dpp v1, v30, v74 quad_perm:[3,3,3,3] row_mask:0xf bank_mask:0xf
	v_fmac_f32_dpp v1, v31, v75 quad_perm:[3,3,3,3] row_mask:0xf bank_mask:0xf
	v_fmac_f32_dpp v1, v32, v76 quad_perm:[3,3,3,3] row_mask:0xf bank_mask:0xf
	v_fmac_f32_dpp v1, v33, v77 quad_perm:[3,3,3,3] row_mask:0xf bank_mask:0xf
	global_load_dwordx4 v[30:33], v28, s[8:9] offset:64
	s_waitcnt vmcnt(7)
	v_fmac_f32_dpp v1, v34, v78 quad_perm:[0,0,0,0] row_mask:0xf bank_mask:0xf
	v_fmac_f32_dpp v1, v35, v79 quad_perm:[0,0,0,0] row_mask:0xf bank_mask:0xf
	v_fmac_f32_dpp v1, v36, v80 quad_perm:[0,0,0,0] row_mask:0xf bank_mask:0xf
	v_fmac_f32_dpp v1, v37, v81 quad_perm:[0,0,0,0] row_mask:0xf bank_mask:0xf
	v_fmac_f32_dpp v1, v34, v82 quad_perm:[1,1,1,1] row_mask:0xf bank_mask:0xf
	v_fmac_f32_dpp v1, v35, v83 quad_perm:[1,1,1,1] row_mask:0xf bank_mask:0xf
	v_fmac_f32_dpp v1, v36, v85 quad_perm:[1,1,1,1] row_mask:0xf bank_mask:0xf
	v_fmac_f32_dpp v1, v37, v86 quad_perm:[1,1,1,1] row_mask:0xf bank_mask:0xf
	v_fmac_f32_dpp v1, v34, v87 quad_perm:[2,2,2,2] row_mask:0xf bank_mask:0xf
	v_fmac_f32_dpp v1, v35, v88 quad_perm:[2,2,2,2] row_mask:0xf bank_mask:0xf
	v_fmac_f32_dpp v1, v36, v89 quad_perm:[2,2,2,2] row_mask:0xf bank_mask:0xf
	v_fmac_f32_dpp v1, v37, v90 quad_perm:[2,2,2,2] row_mask:0xf bank_mask:0xf
	v_fmac_f32_dpp v1, v34, v91 quad_perm:[3,3,3,3] row_mask:0xf bank_mask:0xf
	v_fmac_f32_dpp v1, v35, v92 quad_perm:[3,3,3,3] row_mask:0xf bank_mask:0xf
	v_fmac_f32_dpp v1, v36, v93 quad_perm:[3,3,3,3] row_mask:0xf bank_mask:0xf
	v_fmac_f32_dpp v1, v37, v94 quad_perm:[3,3,3,3] row_mask:0xf bank_mask:0xf
	global_load_dwordx4 v[34:37], v28, s[8:9] offset:128
	s_waitcnt vmcnt(7)
	v_fmac_f32_dpp v1, v38, v95 quad_perm:[0,0,0,0] row_mask:0xf bank_mask:0xf
	v_fmac_f32_dpp v1, v39, v96 quad_perm:[0,0,0,0] row_mask:0xf bank_mask:0xf
	v_fmac_f32_dpp v1, v40, v97 quad_perm:[0,0,0,0] row_mask:0xf bank_mask:0xf
	v_fmac_f32_dpp v1, v41, v98 quad_perm:[0,0,0,0] row_mask:0xf bank_mask:0xf
	v_fmac_f32_dpp v1, v38, v99 quad_perm:[1,1,1,1] row_mask:0xf bank_mask:0xf
	v_fmac_f32_dpp v1, v39, v100 quad_perm:[1,1,1,1] row_mask:0xf bank_mask:0xf
	v_fmac_f32_dpp v1, v40, v101 quad_perm:[1,1,1,1] row_mask:0xf bank_mask:0xf
	v_fmac_f32_dpp v1, v41, v102 quad_perm:[1,1,1,1] row_mask:0xf bank_mask:0xf
	v_fmac_f32_dpp v1, v38, v103 quad_perm:[2,2,2,2] row_mask:0xf bank_mask:0xf
	v_fmac_f32_dpp v1, v39, v104 quad_perm:[2,2,2,2] row_mask:0xf bank_mask:0xf
	v_fmac_f32_dpp v1, v40, v105 quad_perm:[2,2,2,2] row_mask:0xf bank_mask:0xf
	v_fmac_f32_dpp v1, v41, v106 quad_perm:[2,2,2,2] row_mask:0xf bank_mask:0xf
	v_fmac_f32_dpp v1, v38, v107 quad_perm:[3,3,3,3] row_mask:0xf bank_mask:0xf
	v_fmac_f32_dpp v1, v39, v108 quad_perm:[3,3,3,3] row_mask:0xf bank_mask:0xf
	v_fmac_f32_dpp v1, v40, v109 quad_perm:[3,3,3,3] row_mask:0xf bank_mask:0xf
	v_fmac_f32_dpp v1, v41, v110 quad_perm:[3,3,3,3] row_mask:0xf bank_mask:0xf
	global_load_dwordx4 v[38:41], v28, s[8:9] offset:192
	s_waitcnt vmcnt(7)
	v_fmac_f32_dpp v1, v42, v111 quad_perm:[0,0,0,0] row_mask:0xf bank_mask:0xf
	v_fmac_f32_dpp v1, v43, v112 quad_perm:[0,0,0,0] row_mask:0xf bank_mask:0xf
	v_fmac_f32_dpp v1, v44, v113 quad_perm:[0,0,0,0] row_mask:0xf bank_mask:0xf
	v_fmac_f32_dpp v1, v45, v114 quad_perm:[0,0,0,0] row_mask:0xf bank_mask:0xf
	v_fmac_f32_dpp v1, v42, v115 quad_perm:[1,1,1,1] row_mask:0xf bank_mask:0xf
	v_fmac_f32_dpp v1, v43, v116 quad_perm:[1,1,1,1] row_mask:0xf bank_mask:0xf
	v_fmac_f32_dpp v1, v44, v117 quad_perm:[1,1,1,1] row_mask:0xf bank_mask:0xf
	v_fmac_f32_dpp v1, v45, v118 quad_perm:[1,1,1,1] row_mask:0xf bank_mask:0xf
	v_fmac_f32_dpp v1, v42, v119 quad_perm:[2,2,2,2] row_mask:0xf bank_mask:0xf
	v_fmac_f32_dpp v1, v43, v120 quad_perm:[2,2,2,2] row_mask:0xf bank_mask:0xf
	v_fmac_f32_dpp v1, v44, v121 quad_perm:[2,2,2,2] row_mask:0xf bank_mask:0xf
	v_fmac_f32_dpp v1, v45, v122 quad_perm:[2,2,2,2] row_mask:0xf bank_mask:0xf
	v_fmac_f32_dpp v1, v42, v123 quad_perm:[3,3,3,3] row_mask:0xf bank_mask:0xf
	v_fmac_f32_dpp v1, v43, v124 quad_perm:[3,3,3,3] row_mask:0xf bank_mask:0xf
	v_fmac_f32_dpp v1, v44, v125 quad_perm:[3,3,3,3] row_mask:0xf bank_mask:0xf
	v_fmac_f32_dpp v1, v45, v126 quad_perm:[3,3,3,3] row_mask:0xf bank_mask:0xf
	global_load_dwordx4 v[42:45], v28, s[8:9] offset:256
	s_waitcnt vmcnt(7)
	v_fmac_f32_dpp v1, v178, v127 quad_perm:[0,0,0,0] row_mask:0xf bank_mask:0xf
	v_fmac_f32_dpp v1, v179, v128 quad_perm:[0,0,0,0] row_mask:0xf bank_mask:0xf
	v_fmac_f32_dpp v1, v180, v129 quad_perm:[0,0,0,0] row_mask:0xf bank_mask:0xf
	v_fmac_f32_dpp v1, v181, v130 quad_perm:[0,0,0,0] row_mask:0xf bank_mask:0xf
	v_fmac_f32_dpp v1, v178, v131 quad_perm:[1,1,1,1] row_mask:0xf bank_mask:0xf
	v_fmac_f32_dpp v1, v179, v132 quad_perm:[1,1,1,1] row_mask:0xf bank_mask:0xf
	v_fmac_f32_dpp v1, v180, v133 quad_perm:[1,1,1,1] row_mask:0xf bank_mask:0xf
	v_fmac_f32_dpp v1, v181, v134 quad_perm:[1,1,1,1] row_mask:0xf bank_mask:0xf
	v_fmac_f32_dpp v1, v178, v135 quad_perm:[2,2,2,2] row_mask:0xf bank_mask:0xf
	v_fmac_f32_dpp v1, v179, v136 quad_perm:[2,2,2,2] row_mask:0xf bank_mask:0xf
	v_fmac_f32_dpp v1, v180, v137 quad_perm:[2,2,2,2] row_mask:0xf bank_mask:0xf
	v_fmac_f32_dpp v1, v181, v140 quad_perm:[2,2,2,2] row_mask:0xf bank_mask:0xf
	v_fmac_f32_dpp v1, v178, v141 quad_perm:[3,3,3,3] row_mask:0xf bank_mask:0xf
	v_fmac_f32_dpp v1, v179, v142 quad_perm:[3,3,3,3] row_mask:0xf bank_mask:0xf
	v_fmac_f32_dpp v1, v180, v143 quad_perm:[3,3,3,3] row_mask:0xf bank_mask:0xf
	v_fmac_f32_dpp v1, v181, v144 quad_perm:[3,3,3,3] row_mask:0xf bank_mask:0xf
	global_load_dwordx4 v[178:181], v28, s[8:9] offset:320
	s_waitcnt vmcnt(7)
	v_fmac_f32_dpp v1, v182, v145 quad_perm:[0,0,0,0] row_mask:0xf bank_mask:0xf
	v_fmac_f32_dpp v1, v183, v146 quad_perm:[0,0,0,0] row_mask:0xf bank_mask:0xf
	v_fmac_f32_dpp v1, v184, v147 quad_perm:[0,0,0,0] row_mask:0xf bank_mask:0xf
	v_fmac_f32_dpp v1, v185, v148 quad_perm:[0,0,0,0] row_mask:0xf bank_mask:0xf
	v_fmac_f32_dpp v1, v182, v149 quad_perm:[1,1,1,1] row_mask:0xf bank_mask:0xf
	v_fmac_f32_dpp v1, v183, v150 quad_perm:[1,1,1,1] row_mask:0xf bank_mask:0xf
	v_fmac_f32_dpp v1, v184, v151 quad_perm:[1,1,1,1] row_mask:0xf bank_mask:0xf
	v_fmac_f32_dpp v1, v185, v152 quad_perm:[1,1,1,1] row_mask:0xf bank_mask:0xf
	v_fmac_f32_dpp v1, v182, v153 quad_perm:[2,2,2,2] row_mask:0xf bank_mask:0xf
	v_fmac_f32_dpp v1, v183, v154 quad_perm:[2,2,2,2] row_mask:0xf bank_mask:0xf
	v_fmac_f32_dpp v1, v184, v156 quad_perm:[2,2,2,2] row_mask:0xf bank_mask:0xf
	v_fmac_f32_dpp v1, v185, v157 quad_perm:[2,2,2,2] row_mask:0xf bank_mask:0xf
	v_fmac_f32_dpp v1, v182, v158 quad_perm:[3,3,3,3] row_mask:0xf bank_mask:0xf
	v_fmac_f32_dpp v1, v183, v159 quad_perm:[3,3,3,3] row_mask:0xf bank_mask:0xf
	v_fmac_f32_dpp v1, v184, v160 quad_perm:[3,3,3,3] row_mask:0xf bank_mask:0xf
	v_fmac_f32_dpp v1, v185, v161 quad_perm:[3,3,3,3] row_mask:0xf bank_mask:0xf
	global_load_dwordx4 v[182:185], v28, s[8:9] offset:384
	s_waitcnt vmcnt(7)
	v_fmac_f32_dpp v1, v244, v162 quad_perm:[0,0,0,0] row_mask:0xf bank_mask:0xf
	v_fmac_f32_dpp v1, v245, v163 quad_perm:[0,0,0,0] row_mask:0xf bank_mask:0xf
	v_fmac_f32_dpp v1, v246, v164 quad_perm:[0,0,0,0] row_mask:0xf bank_mask:0xf
	v_fmac_f32_dpp v1, v247, v165 quad_perm:[0,0,0,0] row_mask:0xf bank_mask:0xf
	v_fmac_f32_dpp v1, v244, v166 quad_perm:[1,1,1,1] row_mask:0xf bank_mask:0xf
	v_fmac_f32_dpp v1, v245, v167 quad_perm:[1,1,1,1] row_mask:0xf bank_mask:0xf
	v_fmac_f32_dpp v1, v246, v168 quad_perm:[1,1,1,1] row_mask:0xf bank_mask:0xf
	v_fmac_f32_dpp v1, v247, v169 quad_perm:[1,1,1,1] row_mask:0xf bank_mask:0xf
	v_fmac_f32_dpp v1, v244, v170 quad_perm:[2,2,2,2] row_mask:0xf bank_mask:0xf
	v_fmac_f32_dpp v1, v245, v171 quad_perm:[2,2,2,2] row_mask:0xf bank_mask:0xf
	v_fmac_f32_dpp v1, v246, v172 quad_perm:[2,2,2,2] row_mask:0xf bank_mask:0xf
	v_fmac_f32_dpp v1, v247, v173 quad_perm:[2,2,2,2] row_mask:0xf bank_mask:0xf
	v_fmac_f32_dpp v1, v244, v174 quad_perm:[3,3,3,3] row_mask:0xf bank_mask:0xf
	v_fmac_f32_dpp v1, v245, v175 quad_perm:[3,3,3,3] row_mask:0xf bank_mask:0xf
	v_fmac_f32_dpp v1, v246, v176 quad_perm:[3,3,3,3] row_mask:0xf bank_mask:0xf
	v_fmac_f32_dpp v1, v247, v177 quad_perm:[3,3,3,3] row_mask:0xf bank_mask:0xf
	global_load_dwordx4 v[244:247], v28, s[8:9] offset:448
	v_cvt_pk_bf16_f32 v24, v0, v1
	v_mov_b32_e32 v2, v3
	v_mov_b32_e32 v3, v4
	v_mov_b32_e32 v4, v5
	v_mov_b32_e32 v5, v6
	v_mov_b32_e32 v6, v7
	v_mov_b32_e32 v7, v8
	v_mov_b32_e32 v8, v9
	v_mov_b32_e32 v9, v24
	s_add_u32 s52, s52, 0x400
	s_addc_u32 s53, s53, 0
	s_add_i32 s30, s30, 1
	s_cmp_lt_u32 s30, 8
	s_cbranch_scc1 .Lwf_fold_loop
	s_waitcnt vmcnt(0)
	global_store_dwordx4 v27, v[2:5], s[54:55]
	global_store_dwordx4 v27, v[6:9], s[54:55] offset:16
	s_movk_i32 s68, 0x2000
	s_movk_i32 s69, 0x60
	s_mov_b64 s[36:37], 0x1200
	s_mov_b64 s[38:39], 0x1400
	s_mov_b64 s[40:41], 0x1600
	s_mov_b64 s[42:43], 0x1800
	s_mov_b64 s[44:45], 0x1a00
	s_mov_b64 s[46:47], 0x1c00
	s_mov_b64 s[48:49], 0x1e00
	s_movk_i32 s70, 0x2400
	s_movk_i32 s71, 0x400
	s_movk_i32 s72, 0xfc00
	s_mov_b32 s73, 0xbfb8aa3b
	s_mov_b32 s74, 0x42ce8ed0
	s_mov_b32 s75, 0xc2b17218
	s_movk_i32 s76, 0xfbff
	s_movk_i32 s77, 0x21ff
	s_movk_i32 s78, 0x6000
	s_mov_b32 s79, 0x18000
	s_mov_b32 s80, 0x30000
	s_mov_b32 s81, 0x48000
	s_mov_b32 s82, 0x60000
	s_mov_b32 s83, 0x78000
	s_load_dword s6, s[0:1], 0x4c8
	s_waitcnt lgkmcnt(0)
	s_add_i32 s89, s89, s6
	s_cmp_ge_i32 s89, s62
	s_cbranch_scc1 .LBB0_113
	s_branch .LBB0_24
